# P54a: attention QK^T LDS reads issued up front with counted lgkmcnt waits (12 deep comp A, 9 deep comp B)
# baseline (speedup 1.0000x reference)
.LBB0_702:
	v_add_u32_e32 v130, s98, v221
	v_add_u32_e32 v206, s3, v212
	v_add_u32_e32 v138, v206, v220
	ds_read_b128 v[146:149], v130 offset:32768
	ds_read_b128 v[134:137], v221
	ds_read_b128 v[130:133], v138 offset:40960
	v_add_u32_e32 v207, s98, v222
	v_add_u32_e32 v139, v206, v213
	ds_read_b128 v[208:211], v207 offset:32768
	ds_read_b128 v[232:235], v222
	ds_read_b128 v[162:165], v139 offset:40960
	v_add_u32_e32 v207, s98, v223
	v_add_u32_e32 v139, v206, v214
	ds_read_b128 v[166:169], v207 offset:32768
	ds_read_b128 v[170:173], v223
	ds_read_b128 v[174:177], v139 offset:40960
	v_add_u32_e32 v207, s98, v224
	v_add_u32_e32 v139, v206, v215
	ds_read_b128 v[178:181], v207 offset:32768
	ds_read_b128 v[182:185], v224
	ds_read_b128 v[186:189], v139 offset:40960
	s_cmp_lg_u32 s40, 0
	s_cselect_b64 s[8:9], -1, 0
	s_cmp_eq_u32 s40, 0
	s_waitcnt lgkmcnt(10)
	v_mfma_f32_32x32x16_bf16 v[146:161], v[146:149], v[134:137], 0
	s_waitcnt lgkmcnt(9)
	v_mfma_f32_32x32x16_bf16 v[130:145], v[130:133], v[134:137], 0
	s_waitcnt lgkmcnt(7)
	v_mfma_f32_32x32x16_bf16 v[146:161], v[208:211], v[232:235], v[146:161]
	s_waitcnt lgkmcnt(6)
	v_mfma_f32_32x32x16_bf16 v[130:145], v[162:165], v[232:235], v[130:145]
	s_waitcnt lgkmcnt(4)
	v_mfma_f32_32x32x16_bf16 v[146:161], v[166:169], v[170:173], v[146:161]
	s_waitcnt lgkmcnt(3)
	v_mfma_f32_32x32x16_bf16 v[130:145], v[174:177], v[170:173], v[130:145]
	s_waitcnt lgkmcnt(1)
	v_mfma_f32_32x32x16_bf16 v[146:161], v[178:181], v[182:185], v[146:161]
	s_waitcnt lgkmcnt(0)
	v_mfma_f32_32x32x16_bf16 v[130:145], v[186:189], v[182:185], v[130:145]
	s_cbranch_scc1 .LBB0_724
	s_mov_b64 s[6:7], -1
	s_cbranch_execnz .LBB0_705

.LBB0_712:
	s_andn2_b64 vcc, exec, s[10:11]
	s_cbranch_vccnz .LBB0_719
	s_nop 2
	v_add_u32_e32 v130, s98, v225
	v_add_u32_e32 v138, v206, v216
	ds_read_b128 v[146:149], v130 offset:32768
	ds_read_b128 v[134:137], v225
	ds_read_b128 v[130:133], v138 offset:40960
	v_add_u32_e32 v207, s98, v226
	v_add_u32_e32 v139, v206, v217
	ds_read_b128 v[208:211], v207 offset:32768
	ds_read_b128 v[232:235], v226
	ds_read_b128 v[178:181], v139 offset:40960
	v_add_u32_e32 v207, s98, v227
	v_add_u32_e32 v139, v206, v218
	ds_read_b128 v[182:185], v207 offset:32768
	ds_read_b128 v[186:189], v227
	ds_read_b128 v[190:193], v139 offset:40960
	v_add_u32_e32 v207, s98, v228
	v_add_u32_e32 v206, v206, v219
	s_andn2_b64 vcc, exec, s[8:9]
	s_waitcnt lgkmcnt(7)
	v_mfma_f32_32x32x16_bf16 v[146:161], v[146:149], v[134:137], 0
	s_waitcnt lgkmcnt(6)
	v_mfma_f32_32x32x16_bf16 v[130:145], v[130:133], v[134:137], 0
	s_waitcnt lgkmcnt(4)
	v_mfma_f32_32x32x16_bf16 v[146:161], v[208:211], v[232:235], v[146:161]
	s_waitcnt lgkmcnt(3)
	v_mfma_f32_32x32x16_bf16 v[130:145], v[178:181], v[232:235], v[130:145]
	ds_read_b128 v[208:211], v207 offset:32768
	ds_read_b128 v[232:235], v228
	ds_read_b128 v[178:181], v206 offset:40960
	s_waitcnt lgkmcnt(4)
	v_mfma_f32_32x32x16_bf16 v[146:161], v[182:185], v[186:189], v[146:161]
	s_waitcnt lgkmcnt(3)
	v_mfma_f32_32x32x16_bf16 v[130:145], v[190:193], v[186:189], v[130:145]
	s_waitcnt lgkmcnt(1)
	v_mfma_f32_32x32x16_bf16 v[146:161], v[208:211], v[232:235], v[146:161]
	s_waitcnt lgkmcnt(0)
	v_mfma_f32_32x32x16_bf16 v[130:145], v[178:181], v[232:235], v[130:145]
	s_cbranch_vccnz .LBB0_725
	s_mov_b64 s[6:7], -1
	s_cbranch_execnz .LBB0_716
